# phase C compressed branch QK: 16 MFMAs into distinct quads followed by the scale multiplies, the eight s_nop 7 pads removed
# speedup vs baseline: 1.0013x; 1.0013x over previous
; #define MFMA16(a, b, c) __builtin_amdgcn_mfma_f32_16x16x32_bf16((a), (b), (c), 0, 0, 0)
; DI void nsa_wave(const Params& p, int layer, int b, int g, int t0, unsigned char* lds, bf16_t* ybase) {
;     ...
;     for (int kt = 0; kt < 8; ++kt) {
;       const bf16_t* kp = Kc + (long)(kt * 16 + qi) * 64 + quad * 8;
;       sc[kt] = MFMA16(ld8(kp), q0, ((f32x4){0.f, 0.f, 0.f, 0.f}));
;       sc[kt] = MFMA16(ld8(kp + 32), q1, sc[kt]);
;       sc[kt] = sc[kt] * SC;
;     }
.LBB0_708:
	s_mov_b64 s[0:1], -1
	s_andn2_b64 vcc, exec, s[64:65]
	s_waitcnt vmcnt(0)
	v_mov_b32_e32 v174, v220
	v_mfma_f32_16x16x32_bf16 v[200:203], v[38:41], v[216:219], 0
	v_mfma_f32_16x16x32_bf16 v[200:203], v[2:5], v[246:249], v[200:203]
	v_mfma_f32_16x16x32_bf16 v[196:199], v[6:9], v[216:219], 0
	v_mfma_f32_16x16x32_bf16 v[196:199], v[10:13], v[246:249], v[196:199]
	v_mfma_f32_16x16x32_bf16 v[192:195], v[14:17], v[216:219], 0
	v_mfma_f32_16x16x32_bf16 v[192:195], v[18:21], v[246:249], v[192:195]
	v_mfma_f32_16x16x32_bf16 v[188:191], v[22:25], v[216:219], 0
	v_mfma_f32_16x16x32_bf16 v[188:191], v[26:29], v[246:249], v[188:191]
	v_mfma_f32_16x16x32_bf16 v[184:187], v[46:49], v[216:219], 0
	v_mfma_f32_16x16x32_bf16 v[184:187], v[30:33], v[246:249], v[184:187]
	v_mfma_f32_16x16x32_bf16 v[180:183], v[34:37], v[216:219], 0
	v_mfma_f32_16x16x32_bf16 v[180:183], v[42:45], v[246:249], v[180:183]
	v_mfma_f32_16x16x32_bf16 v[176:179], v[50:53], v[216:219], 0
	v_mfma_f32_16x16x32_bf16 v[176:179], v[54:57], v[246:249], v[176:179]
	v_mfma_f32_16x16x32_bf16 v[220:223], v[58:61], v[216:219], 0
	v_mfma_f32_16x16x32_bf16 v[220:223], v[62:65], v[246:249], v[220:223]
	v_pk_mul_f32 v[204:205], v[202:203], s[34:35] op_sel_hi:[1,0]
	v_pk_mul_f32 v[206:207], v[200:201], s[34:35] op_sel_hi:[1,0]
	v_pk_mul_f32 v[200:201], v[198:199], s[34:35] op_sel_hi:[1,0]
	v_pk_mul_f32 v[202:203], v[196:197], s[34:35] op_sel_hi:[1,0]
	v_pk_mul_f32 v[196:197], v[194:195], s[34:35] op_sel_hi:[1,0]
	v_pk_mul_f32 v[198:199], v[192:193], s[34:35] op_sel_hi:[1,0]
	v_pk_mul_f32 v[192:193], v[190:191], s[34:35] op_sel_hi:[1,0]
	v_pk_mul_f32 v[194:195], v[188:189], s[34:35] op_sel_hi:[1,0]
	v_pk_mul_f32 v[188:189], v[186:187], s[34:35] op_sel_hi:[1,0]
	v_pk_mul_f32 v[190:191], v[184:185], s[34:35] op_sel_hi:[1,0]
	v_pk_mul_f32 v[184:185], v[182:183], s[34:35] op_sel_hi:[1,0]
	v_pk_mul_f32 v[186:187], v[180:181], s[34:35] op_sel_hi:[1,0]
	v_pk_mul_f32 v[180:181], v[178:179], s[34:35] op_sel_hi:[1,0]
	v_pk_mul_f32 v[182:183], v[176:177], s[34:35] op_sel_hi:[1,0]
	v_pk_mul_f32 v[176:177], v[222:223], s[34:35] op_sel_hi:[1,0]
	v_pk_mul_f32 v[178:179], v[220:221], s[34:35] op_sel_hi:[1,0]
	s_cbranch_vccnz .LBB0_710
	s_mov_b64 s[0:1], 0
